# lever 8: LDS fragment reads software-pipelined in the retention forward scan (phase 7) as well as the HGRN2 scan (phase 14)
# speedup vs baseline: 1.0075x; 1.0075x over previous
.LBB0_1046:
	v_mov_b32_e32 v37, v34
	v_mov_b32_e32 v34, v33
	v_mov_b32_e32 v36, v32
	v_pk_mul_f32 v[32:33], v[80:81], v[34:35]
	v_mov_b32_e32 v34, v38
	v_mov_b32_e32 v35, v40
	v_pk_mul_f32 v[36:37], v[80:81], v[36:37]
	v_pk_mul_f32 v[34:35], v[80:81], v[34:35]
	v_cvt_pk_bf16_f32 v36, v36, v37
	v_mov_b32_e32 v40, v39
	v_cvt_pk_bf16_f32 v37, v34, v35
	v_mov_b32_e32 v34, v42
	v_mov_b32_e32 v35, v44
	v_mov_b32_e32 v44, v43
	v_pk_mul_f32 v[38:39], v[80:81], v[40:41]
	v_pk_mul_f32 v[34:35], v[80:81], v[34:35]
	v_pk_mul_f32 v[40:41], v[80:81], v[44:45]
	v_cvt_pk_bf16_f32 v32, v32, v33
	v_cvt_pk_bf16_f32 v33, v38, v39
	v_cvt_pk_bf16_f32 v38, v34, v35
	v_cvt_pk_bf16_f32 v34, v40, v41
	v_mov_b32_e32 v40, v46
	v_mov_b32_e32 v41, v48
	v_pk_mul_f32 v[40:41], v[80:81], v[40:41]
	v_mov_b32_e32 v48, v47
	v_pk_mul_f32 v[42:43], v[80:81], v[48:49]
	v_cvt_pk_bf16_f32 v39, v40, v41
	v_mov_b32_e32 v40, v50
	v_mov_b32_e32 v41, v52
	v_mov_b32_e32 v52, v51
	v_cvt_pk_bf16_f32 v35, v42, v43
	v_pk_mul_f32 v[40:41], v[80:81], v[40:41]
	v_pk_mul_f32 v[42:43], v[80:81], v[52:53]
	v_cvt_pk_bf16_f32 v44, v40, v41
	v_cvt_pk_bf16_f32 v40, v42, v43
	v_mov_b32_e32 v42, v54
	v_mov_b32_e32 v43, v56
	v_pk_mul_f32 v[42:43], v[80:81], v[42:43]
	v_mov_b32_e32 v56, v55
	v_cvt_pk_bf16_f32 v45, v42, v43
	v_mov_b32_e32 v42, v58
	v_mov_b32_e32 v43, v60
	v_mov_b32_e32 v60, v59
	v_pk_mul_f32 v[46:47], v[80:81], v[56:57]
	v_pk_mul_f32 v[42:43], v[80:81], v[42:43]
	v_pk_mul_f32 v[48:49], v[80:81], v[60:61]
	v_cvt_pk_bf16_f32 v41, v46, v47
	v_cvt_pk_bf16_f32 v46, v42, v43
	v_cvt_pk_bf16_f32 v42, v48, v49
	v_mov_b32_e32 v48, v62
	v_mov_b32_e32 v49, v90
	v_mov_b32_e32 v90, v63
	v_pk_mul_f32 v[48:49], v[80:81], v[48:49]
	v_pk_mul_f32 v[50:51], v[80:81], v[90:91]
	v_cvt_pk_bf16_f32 v47, v48, v49
	v_cvt_pk_bf16_f32 v43, v50, v51
	s_waitcnt lgkmcnt(0)
	s_barrier
	s_waitcnt lgkmcnt(0)
	ds_read_b128 v[196:199], v97
	v_add_u32_e32 v52, v98, v100
	s_add_i32 s50, s50, -1
	s_add_i32 s54, s54, 1
	s_cmp_lg_u32 s50, -2
	s_waitcnt lgkmcnt(0)
	v_pk_mul_f32 v[48:49], v[4:5], v[196:197]
	v_pk_mul_f32 v[50:51], v[6:7], v[198:199]
	v_cvt_pk_bf16_f32 v48, v48, v49
	v_cvt_pk_bf16_f32 v49, v50, v51
	ds_write_b64 v52, v[48:49] offset:45056
	ds_read_b128 v[200:203], v97 offset:64
	s_waitcnt lgkmcnt(0)
	v_pk_mul_f32 v[48:49], v[0:1], v[200:201]
	v_pk_mul_f32 v[50:51], v[2:3], v[202:203]
	v_cvt_pk_bf16_f32 v48, v48, v49
	v_cvt_pk_bf16_f32 v49, v50, v51
	ds_write_b64 v123, v[48:49] offset:45056
	ds_read_b128 v[204:207], v97 offset:128
	s_waitcnt lgkmcnt(0)
	v_pk_mul_f32 v[48:49], v[8:9], v[204:205]
	v_pk_mul_f32 v[50:51], v[10:11], v[206:207]
	v_cvt_pk_bf16_f32 v48, v48, v49
	v_cvt_pk_bf16_f32 v49, v50, v51
	ds_write_b64 v124, v[48:49] offset:45056
	ds_read_b128 v[208:211], v97 offset:192
	s_waitcnt lgkmcnt(0)
	v_pk_mul_f32 v[48:49], v[12:13], v[208:209]
	v_pk_mul_f32 v[50:51], v[14:15], v[210:211]
	v_cvt_pk_bf16_f32 v48, v48, v49
	v_cvt_pk_bf16_f32 v49, v50, v51
	ds_write_b64 v125, v[48:49] offset:45056
	ds_read_b128 v[212:215], v97 offset:256
	s_waitcnt lgkmcnt(0)
	v_pk_mul_f32 v[48:49], v[16:17], v[212:213]
	v_pk_mul_f32 v[50:51], v[18:19], v[214:215]
	v_cvt_pk_bf16_f32 v48, v48, v49
	v_cvt_pk_bf16_f32 v49, v50, v51
	ds_write_b64 v52, v[48:49] offset:45184
	ds_read_b128 v[216:219], v97 offset:320
	s_waitcnt lgkmcnt(0)
	v_pk_mul_f32 v[48:49], v[20:21], v[216:217]
	v_pk_mul_f32 v[50:51], v[22:23], v[218:219]
	v_cvt_pk_bf16_f32 v48, v48, v49
	v_cvt_pk_bf16_f32 v49, v50, v51
	ds_write_b64 v52, v[48:49] offset:45216
	ds_read_b128 v[220:223], v97 offset:384
	s_waitcnt lgkmcnt(0)
	v_pk_mul_f32 v[48:49], v[24:25], v[220:221]
	v_pk_mul_f32 v[50:51], v[26:27], v[222:223]
	v_cvt_pk_bf16_f32 v48, v48, v49
	v_cvt_pk_bf16_f32 v49, v50, v51
	ds_write_b64 v52, v[48:49] offset:45248
	ds_read_b128 v[224:227], v97 offset:448
	s_waitcnt lgkmcnt(0)
	v_pk_mul_f32 v[48:49], v[28:29], v[224:225]
	v_pk_mul_f32 v[50:51], v[30:31], v[226:227]
	v_cvt_pk_bf16_f32 v48, v48, v49
	v_cvt_pk_bf16_f32 v49, v50, v51
	ds_write_b64 v52, v[48:49] offset:45280
	ds_read_b128 v[228:231], v126 offset:17408
	ds_read_b128 v[232:235], v126 offset:17472
	ds_read_b128 v[236:239], v126 offset:17536
	ds_read_b128 v[244:247], v126 offset:17600
	ds_read_b128 v[248:251], v126 offset:21824
	ds_read_b128 v[252:255], v126 offset:21760
	v_add_u32_e32 v48, v98, v96
	ds_read_b128 v[60:63], v48
	ds_read_b128 v[52:55], v48 offset:64
	ds_read_b128 v[56:59], v48 offset:128
	ds_read_b128 v[48:51], v48 offset:192
	s_waitcnt lgkmcnt(3)
	v_mfma_f32_16x16x32_bf16 v[172:175], v[228:231], v[60:63], 0
	ds_read_b128 v[196:199], v126 offset:21888
	s_waitcnt lgkmcnt(3)
	v_mfma_f32_16x16x32_bf16 v[172:175], v[232:235], v[52:55], v[172:175]
	ds_read_b128 v[200:203], v126 offset:21952
	s_waitcnt lgkmcnt(3)
	v_mfma_f32_16x16x32_bf16 v[172:175], v[236:239], v[56:59], v[172:175]
	ds_read_b128 v[204:207], v126 offset:26176
	s_waitcnt lgkmcnt(3)
	v_mfma_f32_16x16x32_bf16 v[172:175], v[244:247], v[48:51], v[172:175]
	ds_read_b128 v[208:211], v126 offset:26112
	s_nop 6
	v_cndmask_b32_e64 v64, v172, 0, s[2:3]
	v_cndmask_b32_e64 v77, v173, 0, s[4:5]
	v_cndmask_b32_e64 v89, v174, 0, s[6:7]
	v_cndmask_b32_e64 v91, v175, 0, s[8:9]
	v_mfma_f32_16x16x32_bf16 v[172:175], v[252:255], v[60:63], 0
	ds_read_b128 v[212:215], v126 offset:26240
	v_cvt_pk_bf16_f32 v90, v64, v77
	v_cvt_pk_bf16_f32 v91, v89, v91
	v_mfma_f32_16x16x32_bf16 v[172:175], v[248:251], v[52:55], v[172:175]
	ds_read_b128 v[216:219], v126 offset:26304
	s_waitcnt lgkmcnt(5)
	v_mfma_f32_16x16x32_bf16 v[172:175], v[196:199], v[56:59], v[172:175]
	ds_read_b128 v[220:223], v126 offset:30528
	s_waitcnt lgkmcnt(5)
	v_mfma_f32_16x16x32_bf16 v[172:175], v[200:203], v[48:51], v[172:175]
	ds_read_b128 v[224:227], v126 offset:30464
	s_nop 6
	v_cndmask_b32_e64 v64, v172, 0, s[10:11]
	v_cndmask_b32_e64 v89, v174, 0, s[14:15]
	v_cndmask_b32_e64 v172, v175, 0, s[16:17]
	v_cndmask_b32_e64 v77, v173, 0, s[12:13]
	v_cvt_pk_bf16_f32 v177, v89, v172
	s_waitcnt lgkmcnt(4)
	v_mfma_f32_16x16x32_bf16 v[172:175], v[208:211], v[60:63], 0
	ds_read_b128 v[228:231], v126 offset:30592
	v_cvt_pk_bf16_f32 v176, v64, v77
	v_mfma_f32_16x16x32_bf16 v[172:175], v[204:207], v[52:55], v[172:175]
	s_waitcnt lgkmcnt(4)
	v_mfma_f32_16x16x32_bf16 v[172:175], v[212:215], v[56:59], v[172:175]
	s_waitcnt lgkmcnt(3)
	v_mfma_f32_16x16x32_bf16 v[172:175], v[216:219], v[48:51], v[172:175]
	s_nop 6
	s_nop 0
	v_cndmask_b32_e64 v64, v172, 0, s[18:19]
	v_cndmask_b32_e64 v89, v174, 0, s[22:23]
	v_cndmask_b32_e64 v172, v175, 0, s[24:25]
	v_cndmask_b32_e64 v77, v173, 0, s[20:21]
	v_cvt_pk_bf16_f32 v193, v89, v172
	s_waitcnt lgkmcnt(1)
	v_mfma_f32_16x16x32_bf16 v[172:175], v[224:227], v[60:63], 0
	v_cvt_pk_bf16_f32 v192, v64, v77
	v_mfma_f32_16x16x32_bf16 v[172:175], v[220:223], v[52:55], v[172:175]
	s_waitcnt lgkmcnt(0)
	v_mfma_f32_16x16x32_bf16 v[172:175], v[228:231], v[56:59], v[172:175]
	ds_read_b128 v[188:191], v126 offset:30656
	s_waitcnt lgkmcnt(0)
	s_barrier
	v_mfma_f32_16x16x32_bf16 v[172:175], v[188:191], v[48:51], v[172:175]
	s_nop 7
	v_cndmask_b32_e64 v64, v172, 0, s[26:27]
	v_cndmask_b32_e64 v77, v173, 0, s[28:29]
	v_cvt_pk_bf16_f32 v172, v64, v77
	v_add_u32_e32 v64, v99, v100
	v_cndmask_b32_e64 v89, v174, 0, s[30:31]
	v_cndmask_b32_e64 v173, v175, 0, s[34:35]
	v_add_u32_e32 v64, 0xf000, v64
	v_cvt_pk_bf16_f32 v173, v89, v173
	ds_write2_b64 v64, v[90:91], v[176:177] offset0:128 offset1:132
	ds_write2_b64 v64, v[192:193], v[172:173] offset0:136 offset1:140
	ds_write_b128 v127, v[36:39] offset:17408
	ds_write_b128 v127, v[44:47] offset:17424
	ds_write_b128 v127, v[32:35] offset:17552
	ds_write_b128 v127, v[40:43] offset:17568
	v_ashrrev_i32_e32 v40, 8, v147
	v_cmp_gt_i32_e32 vcc, 32, v40
	v_lshlrev_b32_e32 v40, 1, v40
	v_subrev_u32_e32 v42, 63, v40
	v_or_b32_e32 v40, 1, v40
	v_ashrrev_i32_e32 v41, 31, v40
	v_cndmask_b32_e32 v41, 0, v41, vcc
	v_cndmask_b32_e32 v40, v42, v40, vcc
	v_cndmask_b32_e32 v64, v133, v134, vcc
	v_lshl_add_u64 v[42:43], s[94:95], 0, v[64:65]
	v_lshlrev_b64 v[40:41], 20, v[40:41]
	v_add_u32_e32 v46, v99, v96
	v_lshl_add_u64 v[40:41], v[42:43], 0, v[40:41]
	v_and_b32_e32 v42, 0x7f800, v148
	s_waitcnt lgkmcnt(0)
	s_barrier
	s_waitcnt lgkmcnt(0)
	ds_read_b128 v[196:199], v46 offset:62464
	ds_read_b128 v[200:203], v46 offset:62528
	ds_read_b128 v[204:207], v128 offset:35840
	ds_read_b128 v[208:211], v128 offset:35904
	ds_read_b128 v[212:215], v126 offset:45056
	ds_read_b128 v[216:219], v126 offset:45120
	v_lshlrev_b32_e32 v64, 1, v42
	s_waitcnt lgkmcnt(3)
	v_mfma_f32_16x16x32_bf16 v[42:45], v[204:207], v[196:199], 0
	ds_read_b128 v[220:223], v126 offset:45184
	ds_read_b128 v[224:227], v126 offset:45248
	v_lshl_add_u64 v[40:41], v[40:41], 0, v[64:65]
	v_mov_b32_e32 v89, v65
	v_lshl_add_u64 v[40:41], v[40:41], 0, v[88:89]
	s_waitcnt lgkmcnt(4)
	v_mfma_f32_16x16x32_bf16 v[42:45], v[208:211], v[200:203], v[42:45]
	ds_read_b128 v[228:231], v128 offset:38208
	ds_read_b128 v[232:235], v128 offset:38144
	v_lshl_add_u64 v[40:41], v[78:79], 1, v[40:41]
	v_mov_b32_e32 v77, v65
	s_waitcnt lgkmcnt(5)
	v_mfma_f32_16x16x32_bf16 v[42:45], v[212:215], v[60:63], v[42:45]
	ds_read_b128 v[236:239], v126 offset:49408
	v_lshl_add_u64 v[40:41], v[40:41], 0, v[76:77]
	v_add_u32_e32 v148, 0xfffe0000, v148
	s_waitcnt lgkmcnt(5)
	v_mfma_f32_16x16x32_bf16 v[42:45], v[216:219], v[52:55], v[42:45]
	ds_read_b128 v[244:247], v126 offset:49472
	v_subrev_u32_e32 v147, 64, v147
	s_waitcnt lgkmcnt(5)
	v_mfma_f32_16x16x32_bf16 v[42:45], v[220:223], v[56:59], v[42:45]
	ds_read_b128 v[248:251], v126 offset:49536
	s_waitcnt lgkmcnt(5)
	v_mfma_f32_16x16x32_bf16 v[42:45], v[224:227], v[48:51], v[42:45]
	ds_read_b128 v[252:255], v126 offset:49600
	s_nop 6
	v_cvt_pk_bf16_f32 v42, v42, v43
	v_cvt_pk_bf16_f32 v43, v44, v45
	global_store_dwordx2 v[40:41], v[42:43], off
	s_waitcnt lgkmcnt(4)
	v_mfma_f32_16x16x32_bf16 v[42:45], v[232:235], v[196:199], 0
	ds_read_b128 v[204:207], v128 offset:40512
	v_mfma_f32_16x16x32_bf16 v[42:45], v[228:231], v[200:203], v[42:45]
	ds_read_b128 v[208:211], v128 offset:40448
	s_waitcnt lgkmcnt(5)
	v_mfma_f32_16x16x32_bf16 v[42:45], v[236:239], v[60:63], v[42:45]
	ds_read_b128 v[212:215], v126 offset:53760
	s_waitcnt lgkmcnt(5)
	v_mfma_f32_16x16x32_bf16 v[42:45], v[244:247], v[52:55], v[42:45]
	ds_read_b128 v[216:219], v126 offset:53824
	s_waitcnt lgkmcnt(5)
	v_mfma_f32_16x16x32_bf16 v[42:45], v[248:251], v[56:59], v[42:45]
	ds_read_b128 v[220:223], v126 offset:53888
	s_waitcnt lgkmcnt(5)
	v_mfma_f32_16x16x32_bf16 v[42:45], v[252:255], v[48:51], v[42:45]
	ds_read_b128 v[224:227], v128 offset:42752
	s_nop 6
	v_cvt_pk_bf16_f32 v42, v42, v43
	v_cvt_pk_bf16_f32 v43, v44, v45
	global_store_dwordx2 v[40:41], v[42:43], off offset:32
	s_waitcnt lgkmcnt(4)
	v_mfma_f32_16x16x32_bf16 v[42:45], v[208:211], v[196:199], 0
	ds_read_b128 v[232:235], v126 offset:58112
	v_mfma_f32_16x16x32_bf16 v[42:45], v[204:207], v[200:203], v[42:45]
	ds_read_b128 v[228:231], v126 offset:58176
	s_waitcnt lgkmcnt(5)
	v_mfma_f32_16x16x32_bf16 v[42:45], v[212:215], v[60:63], v[42:45]
	ds_read_b128 v[236:239], v126 offset:58240
	s_waitcnt lgkmcnt(5)
	v_mfma_f32_16x16x32_bf16 v[42:45], v[216:219], v[52:55], v[42:45]
	ds_read_b128 v[244:247], v126 offset:58304
	s_waitcnt lgkmcnt(5)
	v_mfma_f32_16x16x32_bf16 v[42:45], v[220:223], v[56:59], v[42:45]
	ds_read_b128 v[248:251], v101
	ds_read_b128 v[172:175], v126 offset:53952
	s_waitcnt lgkmcnt(0)
	v_mfma_f32_16x16x32_bf16 v[42:45], v[172:175], v[48:51], v[42:45]
	s_nop 7
	v_cvt_pk_bf16_f32 v42, v42, v43
	v_cvt_pk_bf16_f32 v43, v44, v45
	global_store_dwordx2 v[40:41], v[42:43], off offset:64
	v_mfma_f32_16x16x32_bf16 v[36:39], v[224:227], v[196:199], 0
	ds_read_b128 v[252:255], v128 offset:17408
	ds_read_b128 v[42:45], v128 offset:42816
	s_waitcnt lgkmcnt(0)
	v_mfma_f32_16x16x32_bf16 v[32:35], v[42:45], v[200:203], v[36:39]
	s_nop 4
	v_mfma_f32_16x16x32_bf16 v[32:35], v[232:235], v[60:63], v[32:35]
	ds_read_b128 v[208:211], v128 offset:17472
	v_mfma_f32_16x16x32_bf16 v[32:35], v[228:231], v[52:55], v[32:35]
	ds_read_b128 v[204:207], v101 offset:64
	v_mfma_f32_16x16x32_bf16 v[32:35], v[236:239], v[56:59], v[32:35]
	ds_read_b128 v[212:215], v128 offset:19712
	v_mfma_f32_16x16x32_bf16 v[32:35], v[244:247], v[48:51], v[32:35]
	ds_read_b128 v[216:219], v128 offset:19776
	s_nop 7
	v_cvt_pk_bf16_f32 v32, v32, v33
	v_cvt_pk_bf16_f32 v33, v34, v35
	global_store_dwordx2 v[40:41], v[32:33], off offset:96
	ds_read_b128 v[36:39], v46 offset:35840
	ds_read_b128 v[32:35], v46 offset:35904
	v_pk_mul_f32 v[4:5], v[4:5], v[248:249]
	ds_read_b128 v[220:223], v101 offset:128
	v_pk_mul_f32 v[6:7], v[6:7], v[250:251]
	s_waitcnt lgkmcnt(2)
	s_nop 0
	v_mfma_f32_16x16x32_bf16 v[4:7], v[252:255], v[36:39], v[4:7]
	ds_read_b128 v[196:199], v128 offset:22016
	s_waitcnt lgkmcnt(2)
	v_mfma_f32_16x16x32_bf16 v[4:7], v[208:211], v[32:35], v[4:7]
	ds_read_b128 v[224:227], v128 offset:22080
	v_pk_mul_f32 v[0:1], v[0:1], v[204:205]
	ds_read_b128 v[200:203], v101 offset:192
	v_pk_mul_f32 v[2:3], v[2:3], v[206:207]
	s_nop 1
	v_mfma_f32_16x16x32_bf16 v[0:3], v[212:215], v[36:39], v[0:3]
	ds_read_b128 v[232:235], v128 offset:24320
	v_mfma_f32_16x16x32_bf16 v[0:3], v[216:219], v[32:35], v[0:3]
	ds_read_b128 v[228:231], v128 offset:24384
	s_waitcnt lgkmcnt(5)
	v_pk_mul_f32 v[8:9], v[8:9], v[220:221]
	ds_read_b128 v[236:239], v101 offset:256
	v_pk_mul_f32 v[10:11], v[10:11], v[222:223]
	s_waitcnt lgkmcnt(5)
	s_nop 0
	v_mfma_f32_16x16x32_bf16 v[8:11], v[196:199], v[36:39], v[8:11]
	ds_read_b128 v[244:247], v128 offset:26624
	s_waitcnt lgkmcnt(5)
	v_mfma_f32_16x16x32_bf16 v[8:11], v[224:227], v[32:35], v[8:11]
	ds_read_b128 v[248:251], v128 offset:26688
	s_waitcnt lgkmcnt(5)
	v_pk_mul_f32 v[12:13], v[12:13], v[200:201]
	ds_read_b128 v[252:255], v101 offset:320
	v_pk_mul_f32 v[14:15], v[14:15], v[202:203]
	s_waitcnt lgkmcnt(5)
	s_nop 0
	v_mfma_f32_16x16x32_bf16 v[12:15], v[232:235], v[36:39], v[12:15]
	ds_read_b128 v[208:211], v128 offset:28928
	s_waitcnt lgkmcnt(5)
	v_mfma_f32_16x16x32_bf16 v[12:15], v[228:231], v[32:35], v[12:15]
	ds_read_b128 v[204:207], v128 offset:28992
	s_waitcnt lgkmcnt(5)
	v_pk_mul_f32 v[16:17], v[16:17], v[236:237]
	ds_read_b128 v[212:215], v101 offset:384
	v_pk_mul_f32 v[18:19], v[18:19], v[238:239]
	s_waitcnt lgkmcnt(5)
	s_nop 0
	v_mfma_f32_16x16x32_bf16 v[16:19], v[244:247], v[36:39], v[16:19]
	ds_read_b128 v[216:219], v128 offset:31232
	s_waitcnt lgkmcnt(5)
	v_mfma_f32_16x16x32_bf16 v[16:19], v[248:251], v[32:35], v[16:19]
	ds_read_b128 v[220:223], v128 offset:31296
	s_waitcnt lgkmcnt(5)
	v_pk_mul_f32 v[20:21], v[20:21], v[252:253]
	ds_read_b128 v[196:199], v101 offset:448
	v_pk_mul_f32 v[22:23], v[22:23], v[254:255]
	s_waitcnt lgkmcnt(5)
	s_nop 0
	v_mfma_f32_16x16x32_bf16 v[20:23], v[208:211], v[36:39], v[20:23]
	s_waitcnt lgkmcnt(4)
	v_mfma_f32_16x16x32_bf16 v[20:23], v[204:207], v[32:35], v[20:23]
	s_waitcnt lgkmcnt(3)
	v_pk_mul_f32 v[24:25], v[24:25], v[212:213]
	v_pk_mul_f32 v[26:27], v[26:27], v[214:215]
	s_waitcnt lgkmcnt(2)
	s_nop 0
	v_mfma_f32_16x16x32_bf16 v[24:27], v[216:219], v[36:39], v[24:27]
	s_waitcnt lgkmcnt(1)
	v_mfma_f32_16x16x32_bf16 v[24:27], v[220:223], v[32:35], v[24:27]
	s_waitcnt lgkmcnt(0)
	v_pk_mul_f32 v[28:29], v[28:29], v[196:197]
	v_pk_mul_f32 v[30:31], v[30:31], v[198:199]
	ds_read_b128 v[40:43], v128 offset:33536
	s_waitcnt lgkmcnt(0)
	v_mfma_f32_16x16x32_bf16 v[28:31], v[40:43], v[36:39], v[28:31]
	ds_read_b128 v[36:39], v128 offset:33600
	s_waitcnt lgkmcnt(0)
	s_barrier
	v_mfma_f32_16x16x32_bf16 v[28:31], v[36:39], v[32:35], v[28:31]
	s_cbranch_scc0 .LBB0_1040

.LBB0_1058:
	v_mov_b32_e32 v37, v34
	v_mov_b32_e32 v34, v33
	v_mov_b32_e32 v36, v32
	v_pk_mul_f32 v[32:33], v[76:77], v[34:35]
	v_mov_b32_e32 v34, v38
	v_mov_b32_e32 v35, v40
	v_pk_mul_f32 v[36:37], v[76:77], v[36:37]
	v_pk_mul_f32 v[34:35], v[76:77], v[34:35]
	v_cvt_pk_bf16_f32 v36, v36, v37
	v_mov_b32_e32 v40, v39
	v_cvt_pk_bf16_f32 v37, v34, v35
	v_mov_b32_e32 v34, v42
	v_mov_b32_e32 v35, v44
	v_mov_b32_e32 v44, v43
	v_pk_mul_f32 v[38:39], v[76:77], v[40:41]
	v_pk_mul_f32 v[34:35], v[76:77], v[34:35]
	v_pk_mul_f32 v[40:41], v[76:77], v[44:45]
	v_cvt_pk_bf16_f32 v32, v32, v33
	v_cvt_pk_bf16_f32 v33, v38, v39
	v_cvt_pk_bf16_f32 v38, v34, v35
	v_cvt_pk_bf16_f32 v34, v40, v41
	v_mov_b32_e32 v40, v46
	v_mov_b32_e32 v41, v48
	v_pk_mul_f32 v[40:41], v[76:77], v[40:41]
	v_mov_b32_e32 v48, v47
	v_pk_mul_f32 v[42:43], v[76:77], v[48:49]
	v_cvt_pk_bf16_f32 v39, v40, v41
	v_mov_b32_e32 v40, v50
	v_mov_b32_e32 v41, v52
	v_mov_b32_e32 v52, v51
	v_cvt_pk_bf16_f32 v35, v42, v43
	v_pk_mul_f32 v[40:41], v[76:77], v[40:41]
	v_pk_mul_f32 v[42:43], v[76:77], v[52:53]
	v_cvt_pk_bf16_f32 v44, v40, v41
	v_cvt_pk_bf16_f32 v40, v42, v43
	v_mov_b32_e32 v42, v54
	v_mov_b32_e32 v43, v56
	v_pk_mul_f32 v[42:43], v[76:77], v[42:43]
	v_mov_b32_e32 v56, v55
	v_cvt_pk_bf16_f32 v45, v42, v43
	v_mov_b32_e32 v42, v58
	v_mov_b32_e32 v43, v60
	v_mov_b32_e32 v60, v59
	v_pk_mul_f32 v[46:47], v[76:77], v[56:57]
	v_pk_mul_f32 v[42:43], v[76:77], v[42:43]
	v_pk_mul_f32 v[48:49], v[76:77], v[60:61]
	v_cvt_pk_bf16_f32 v41, v46, v47
	v_cvt_pk_bf16_f32 v46, v42, v43
	v_cvt_pk_bf16_f32 v42, v48, v49
	v_mov_b32_e32 v48, v62
	v_mov_b32_e32 v49, v86
	v_mov_b32_e32 v86, v63
	v_pk_mul_f32 v[48:49], v[76:77], v[48:49]
	v_pk_mul_f32 v[50:51], v[76:77], v[86:87]
	v_cvt_pk_bf16_f32 v47, v48, v49
	v_cvt_pk_bf16_f32 v43, v50, v51
	s_waitcnt lgkmcnt(0)
	s_barrier
	s_waitcnt lgkmcnt(0)
	ds_read_b128 v[196:199], v93
	v_add_u32_e32 v52, v94, v96
	v_add_u32_e32 v60, v94, v91
	s_add_i32 s52, s52, 1
	v_lshl_add_u64 v[78:79], v[78:79], 0, s[48:49]
	s_waitcnt lgkmcnt(0)
	v_pk_mul_f32 v[48:49], v[4:5], v[196:197]
	v_pk_mul_f32 v[50:51], v[6:7], v[198:199]
	v_cvt_pk_bf16_f32 v48, v48, v49
	v_cvt_pk_bf16_f32 v49, v50, v51
	ds_write_b64 v52, v[48:49] offset:45056
	ds_read_b128 v[200:203], v93 offset:64
	v_lshl_add_u64 v[80:81], v[80:81], 0, s[48:49]
	v_lshl_add_u64 v[82:83], v[82:83], 0, s[50:51]
	s_cmp_lg_u32 s52, 32
	s_waitcnt lgkmcnt(0)
	v_pk_mul_f32 v[48:49], v[0:1], v[200:201]
	v_pk_mul_f32 v[50:51], v[2:3], v[202:203]
	v_cvt_pk_bf16_f32 v48, v48, v49
	v_cvt_pk_bf16_f32 v49, v50, v51
	ds_write_b64 v118, v[48:49] offset:45056
	ds_read_b128 v[204:207], v93 offset:128
	s_waitcnt lgkmcnt(0)
	v_pk_mul_f32 v[48:49], v[8:9], v[204:205]
	v_pk_mul_f32 v[50:51], v[10:11], v[206:207]
	v_cvt_pk_bf16_f32 v48, v48, v49
	v_cvt_pk_bf16_f32 v49, v50, v51
	ds_write_b64 v119, v[48:49] offset:45056
	ds_read_b128 v[208:211], v93 offset:192
	s_waitcnt lgkmcnt(0)
	v_pk_mul_f32 v[48:49], v[12:13], v[208:209]
	v_pk_mul_f32 v[50:51], v[14:15], v[210:211]
	v_cvt_pk_bf16_f32 v48, v48, v49
	v_cvt_pk_bf16_f32 v49, v50, v51
	ds_write_b64 v120, v[48:49] offset:45056
	ds_read_b128 v[212:215], v93 offset:256
	s_waitcnt lgkmcnt(0)
	v_pk_mul_f32 v[48:49], v[16:17], v[212:213]
	v_pk_mul_f32 v[50:51], v[18:19], v[214:215]
	v_cvt_pk_bf16_f32 v48, v48, v49
	v_cvt_pk_bf16_f32 v49, v50, v51
	ds_write_b64 v52, v[48:49] offset:45184
	ds_read_b128 v[216:219], v93 offset:320
	s_waitcnt lgkmcnt(0)
	v_pk_mul_f32 v[48:49], v[20:21], v[216:217]
	v_pk_mul_f32 v[50:51], v[22:23], v[218:219]
	v_cvt_pk_bf16_f32 v48, v48, v49
	v_cvt_pk_bf16_f32 v49, v50, v51
	ds_write_b64 v52, v[48:49] offset:45216
	ds_read_b128 v[220:223], v93 offset:384
	s_waitcnt lgkmcnt(0)
	v_pk_mul_f32 v[48:49], v[24:25], v[220:221]
	v_pk_mul_f32 v[50:51], v[26:27], v[222:223]
	v_cvt_pk_bf16_f32 v48, v48, v49
	v_cvt_pk_bf16_f32 v49, v50, v51
	ds_write_b64 v52, v[48:49] offset:45248
	ds_read_b128 v[224:227], v93 offset:448
	s_waitcnt lgkmcnt(0)
	v_pk_mul_f32 v[48:49], v[28:29], v[224:225]
	v_pk_mul_f32 v[50:51], v[30:31], v[226:227]
	v_cvt_pk_bf16_f32 v48, v48, v49
	v_cvt_pk_bf16_f32 v49, v50, v51
	ds_write_b64 v52, v[48:49] offset:45280
	ds_read_b128 v[228:231], v121 offset:17408
	ds_read_b128 v[232:235], v121 offset:17472
	ds_read_b128 v[236:239], v121 offset:17536
	ds_read_b128 v[244:247], v121 offset:17600
	ds_read_b128 v[248:251], v121 offset:21824
	ds_read_b128 v[252:255], v121 offset:21760
	ds_read_b128 v[48:51], v60
	ds_read_b128 v[52:55], v60 offset:64
	ds_read_b128 v[56:59], v60 offset:128
	ds_read_b128 v[60:63], v60 offset:192
	s_waitcnt lgkmcnt(3)
	v_mfma_f32_16x16x32_bf16 v[164:167], v[228:231], v[48:51], 0
	ds_read_b128 v[196:199], v121 offset:21888
	s_waitcnt lgkmcnt(3)
	v_mfma_f32_16x16x32_bf16 v[164:167], v[232:235], v[52:55], v[164:167]
	ds_read_b128 v[200:203], v121 offset:21952
	s_waitcnt lgkmcnt(3)
	v_mfma_f32_16x16x32_bf16 v[164:167], v[236:239], v[56:59], v[164:167]
	ds_read_b128 v[204:207], v121 offset:26176
	s_waitcnt lgkmcnt(3)
	v_mfma_f32_16x16x32_bf16 v[164:167], v[244:247], v[60:63], v[164:167]
	ds_read_b128 v[208:211], v121 offset:26112
	s_nop 6
	v_cndmask_b32_e64 v86, v164, 0, s[0:1]
	v_cndmask_b32_e64 v87, 0, v165, s[2:3]
	v_cndmask_b32_e64 v163, v166, 0, s[4:5]
	v_cndmask_b32_e64 v164, v167, 0, s[6:7]
	v_cvt_pk_bf16_f32 v86, v86, v87
	v_cvt_pk_bf16_f32 v87, v163, v164
	v_mfma_f32_16x16x32_bf16 v[164:167], v[252:255], v[48:51], 0
	ds_read_b128 v[212:215], v121 offset:26240
	v_mfma_f32_16x16x32_bf16 v[164:167], v[248:251], v[52:55], v[164:167]
	ds_read_b128 v[216:219], v121 offset:26304
	s_waitcnt lgkmcnt(5)
	v_mfma_f32_16x16x32_bf16 v[164:167], v[196:199], v[56:59], v[164:167]
	ds_read_b128 v[220:223], v121 offset:30528
	s_waitcnt lgkmcnt(5)
	v_mfma_f32_16x16x32_bf16 v[164:167], v[200:203], v[60:63], v[164:167]
	ds_read_b128 v[224:227], v121 offset:30464
	s_nop 6
	v_cndmask_b32_e64 v163, v164, 0, s[8:9]
	v_cndmask_b32_e64 v164, v165, 0, s[10:11]
	v_cndmask_b32_e64 v165, v166, 0, s[12:13]
	v_cndmask_b32_e64 v166, v167, 0, s[14:15]
	v_cvt_pk_bf16_f32 v172, v163, v164
	v_cvt_pk_bf16_f32 v173, v165, v166
	s_waitcnt lgkmcnt(4)
	v_mfma_f32_16x16x32_bf16 v[164:167], v[208:211], v[48:51], 0
	ds_read_b128 v[228:231], v121 offset:30592
	v_mfma_f32_16x16x32_bf16 v[164:167], v[204:207], v[52:55], v[164:167]
	s_waitcnt lgkmcnt(4)
	v_mfma_f32_16x16x32_bf16 v[164:167], v[212:215], v[56:59], v[164:167]
	s_waitcnt lgkmcnt(3)
	v_mfma_f32_16x16x32_bf16 v[164:167], v[216:219], v[60:63], v[164:167]
	s_nop 6
	s_nop 0
	v_cndmask_b32_e64 v163, v164, 0, s[16:17]
	v_cndmask_b32_e64 v164, v165, 0, s[18:19]
	v_cndmask_b32_e64 v165, v166, 0, s[20:21]
	v_cndmask_b32_e64 v166, v167, 0, s[22:23]
	v_cvt_pk_bf16_f32 v174, v163, v164
	v_cvt_pk_bf16_f32 v175, v165, v166
	s_waitcnt lgkmcnt(1)
	v_mfma_f32_16x16x32_bf16 v[164:167], v[224:227], v[48:51], 0
	v_mfma_f32_16x16x32_bf16 v[164:167], v[220:223], v[52:55], v[164:167]
	s_waitcnt lgkmcnt(0)
	v_mfma_f32_16x16x32_bf16 v[164:167], v[228:231], v[56:59], v[164:167]
	ds_read_b128 v[168:171], v121 offset:30656
	s_waitcnt lgkmcnt(0)
	s_barrier
	v_mfma_f32_16x16x32_bf16 v[164:167], v[168:171], v[60:63], v[164:167]
	s_nop 7
	v_cndmask_b32_e64 v163, v164, 0, s[24:25]
	v_cndmask_b32_e64 v164, v165, 0, s[26:27]
	v_cvt_pk_bf16_f32 v164, v163, v164
	v_add_u32_e32 v163, v95, v96
	v_cndmask_b32_e64 v165, v166, 0, s[28:29]
	v_cndmask_b32_e64 v166, v167, 0, s[30:31]
	v_add_u32_e32 v163, 0xf000, v163
	v_cvt_pk_bf16_f32 v165, v165, v166
	ds_write2_b64 v163, v[86:87], v[172:173] offset0:128 offset1:132
	ds_write2_b64 v163, v[174:175], v[164:165] offset0:136 offset1:140
	ds_write_b128 v122, v[36:39] offset:17408
	ds_write_b128 v122, v[44:47] offset:17424
	ds_write_b128 v122, v[32:35] offset:17552
	ds_write_b128 v122, v[40:43] offset:17568
	v_add_u32_e32 v86, v95, v91
	s_waitcnt lgkmcnt(0)
	s_barrier
	s_waitcnt lgkmcnt(0)
	ds_read_b128 v[196:199], v86 offset:62464
	ds_read_b128 v[200:203], v86 offset:62528
	ds_read_b128 v[204:207], v123 offset:35840
	ds_read_b128 v[208:211], v123 offset:35904
	ds_read_b128 v[212:215], v121 offset:45056
	ds_read_b128 v[216:219], v121 offset:45120
	s_waitcnt lgkmcnt(3)
	v_mfma_f32_16x16x32_bf16 v[40:43], v[204:207], v[196:199], 0
	ds_read_b128 v[220:223], v121 offset:45184
	ds_read_b128 v[224:227], v121 offset:45248
	s_waitcnt lgkmcnt(4)
	v_mfma_f32_16x16x32_bf16 v[40:43], v[208:211], v[200:203], v[40:43]
	ds_read_b128 v[228:231], v123 offset:38208
	ds_read_b128 v[232:235], v123 offset:38144
	s_waitcnt lgkmcnt(5)
	v_mfma_f32_16x16x32_bf16 v[40:43], v[212:215], v[48:51], v[40:43]
	ds_read_b128 v[236:239], v121 offset:49408
	s_waitcnt lgkmcnt(5)
	v_mfma_f32_16x16x32_bf16 v[40:43], v[216:219], v[52:55], v[40:43]
	ds_read_b128 v[244:247], v121 offset:49472
	s_waitcnt lgkmcnt(5)
	v_mfma_f32_16x16x32_bf16 v[40:43], v[220:223], v[56:59], v[40:43]
	ds_read_b128 v[248:251], v121 offset:49536
	s_waitcnt lgkmcnt(5)
	v_mfma_f32_16x16x32_bf16 v[40:43], v[224:227], v[60:63], v[40:43]
	ds_read_b128 v[252:255], v121 offset:49600
	s_nop 6
	v_cvt_pk_bf16_f32 v40, v40, v41
	v_cvt_pk_bf16_f32 v41, v42, v43
	global_store_dwordx2 v[84:85], v[40:41], off offset:-64
	s_waitcnt lgkmcnt(4)
	v_mfma_f32_16x16x32_bf16 v[40:43], v[232:235], v[196:199], 0
	ds_read_b128 v[204:207], v123 offset:40512
	v_mfma_f32_16x16x32_bf16 v[40:43], v[228:231], v[200:203], v[40:43]
	ds_read_b128 v[208:211], v123 offset:40448
	s_waitcnt lgkmcnt(5)
	v_mfma_f32_16x16x32_bf16 v[40:43], v[236:239], v[48:51], v[40:43]
	ds_read_b128 v[212:215], v121 offset:53760
	s_waitcnt lgkmcnt(5)
	v_mfma_f32_16x16x32_bf16 v[40:43], v[244:247], v[52:55], v[40:43]
	ds_read_b128 v[216:219], v121 offset:53824
	s_waitcnt lgkmcnt(5)
	v_mfma_f32_16x16x32_bf16 v[40:43], v[248:251], v[56:59], v[40:43]
	ds_read_b128 v[220:223], v121 offset:53888
	s_waitcnt lgkmcnt(5)
	v_mfma_f32_16x16x32_bf16 v[40:43], v[252:255], v[60:63], v[40:43]
	ds_read_b128 v[224:227], v123 offset:42752
	s_nop 6
	v_cvt_pk_bf16_f32 v40, v40, v41
	v_cvt_pk_bf16_f32 v41, v42, v43
	global_store_dwordx2 v[84:85], v[40:41], off offset:-32
	s_waitcnt lgkmcnt(4)
	v_mfma_f32_16x16x32_bf16 v[40:43], v[208:211], v[196:199], 0
	ds_read_b128 v[232:235], v123 offset:42816
	v_mfma_f32_16x16x32_bf16 v[40:43], v[204:207], v[200:203], v[40:43]
	ds_read_b128 v[228:231], v121 offset:58112
	s_waitcnt lgkmcnt(5)
	v_mfma_f32_16x16x32_bf16 v[40:43], v[212:215], v[48:51], v[40:43]
	ds_read_b128 v[236:239], v121 offset:58176
	s_waitcnt lgkmcnt(5)
	v_mfma_f32_16x16x32_bf16 v[40:43], v[216:219], v[52:55], v[40:43]
	ds_read_b128 v[244:247], v121 offset:58240
	s_waitcnt lgkmcnt(5)
	v_mfma_f32_16x16x32_bf16 v[40:43], v[220:223], v[56:59], v[40:43]
	ds_read_b128 v[248:251], v121 offset:58304
	ds_read_b128 v[44:47], v121 offset:53952
	s_waitcnt lgkmcnt(0)
	v_mfma_f32_16x16x32_bf16 v[40:43], v[44:47], v[60:63], v[40:43]
	s_nop 7
	v_cvt_pk_bf16_f32 v40, v40, v41
	v_cvt_pk_bf16_f32 v41, v42, v43
	global_store_dwordx2 v[84:85], v[40:41], off
	v_mfma_f32_16x16x32_bf16 v[32:35], v[224:227], v[196:199], 0
	ds_read_b128 v[252:255], v97
	v_mfma_f32_16x16x32_bf16 v[32:35], v[232:235], v[200:203], v[32:35]
	ds_read_b128 v[208:211], v123 offset:17408
	v_mfma_f32_16x16x32_bf16 v[32:35], v[228:231], v[48:51], v[32:35]
	ds_read_b128 v[204:207], v123 offset:17472
	v_mfma_f32_16x16x32_bf16 v[32:35], v[236:239], v[52:55], v[32:35]
	ds_read_b128 v[212:215], v97 offset:64
	v_mfma_f32_16x16x32_bf16 v[32:35], v[244:247], v[56:59], v[32:35]
	ds_read_b128 v[216:219], v123 offset:19712
	v_mfma_f32_16x16x32_bf16 v[32:35], v[248:251], v[60:63], v[32:35]
	ds_read_b128 v[220:223], v123 offset:19776
	s_nop 7
	v_cvt_pk_bf16_f32 v32, v32, v33
	v_cvt_pk_bf16_f32 v33, v34, v35
	global_store_dwordx2 v[84:85], v[32:33], off offset:32
	ds_read_b128 v[36:39], v86 offset:35840
	ds_read_b128 v[32:35], v86 offset:35904
	v_lshl_add_u64 v[84:85], v[84:85], 0, s[50:51]
	s_waitcnt lgkmcnt(7)
	v_pk_mul_f32 v[4:5], v[4:5], v[252:253]
	ds_read_b128 v[196:199], v97 offset:128
	v_pk_mul_f32 v[6:7], v[6:7], v[254:255]
	s_waitcnt lgkmcnt(2)
	s_nop 0
	v_mfma_f32_16x16x32_bf16 v[4:7], v[208:211], v[36:39], v[4:7]
	ds_read_b128 v[224:227], v123 offset:22016
	s_waitcnt lgkmcnt(2)
	v_mfma_f32_16x16x32_bf16 v[4:7], v[204:207], v[32:35], v[4:7]
	ds_read_b128 v[200:203], v123 offset:22080
	v_pk_mul_f32 v[0:1], v[0:1], v[212:213]
	ds_read_b128 v[232:235], v97 offset:192
	v_pk_mul_f32 v[2:3], v[2:3], v[214:215]
	s_nop 1
	v_mfma_f32_16x16x32_bf16 v[0:3], v[216:219], v[36:39], v[0:3]
	ds_read_b128 v[228:231], v123 offset:24320
	v_mfma_f32_16x16x32_bf16 v[0:3], v[220:223], v[32:35], v[0:3]
	ds_read_b128 v[236:239], v123 offset:24384
	s_waitcnt lgkmcnt(5)
	v_pk_mul_f32 v[8:9], v[8:9], v[196:197]
	ds_read_b128 v[244:247], v97 offset:256
	v_pk_mul_f32 v[10:11], v[10:11], v[198:199]
	s_waitcnt lgkmcnt(5)
	s_nop 0
	v_mfma_f32_16x16x32_bf16 v[8:11], v[224:227], v[36:39], v[8:11]
	ds_read_b128 v[248:251], v123 offset:26624
	s_waitcnt lgkmcnt(5)
	v_mfma_f32_16x16x32_bf16 v[8:11], v[200:203], v[32:35], v[8:11]
	ds_read_b128 v[252:255], v123 offset:26688
	s_waitcnt lgkmcnt(5)
	v_pk_mul_f32 v[12:13], v[12:13], v[232:233]
	ds_read_b128 v[208:211], v97 offset:320
	v_pk_mul_f32 v[14:15], v[14:15], v[234:235]
	s_waitcnt lgkmcnt(5)
	s_nop 0
	v_mfma_f32_16x16x32_bf16 v[12:15], v[228:231], v[36:39], v[12:15]
	ds_read_b128 v[204:207], v123 offset:28928
	s_waitcnt lgkmcnt(5)
	v_mfma_f32_16x16x32_bf16 v[12:15], v[236:239], v[32:35], v[12:15]
	ds_read_b128 v[212:215], v123 offset:28992
	s_waitcnt lgkmcnt(5)
	v_pk_mul_f32 v[16:17], v[16:17], v[244:245]
	ds_read_b128 v[216:219], v97 offset:384
	v_pk_mul_f32 v[18:19], v[18:19], v[246:247]
	s_waitcnt lgkmcnt(5)
	s_nop 0
	v_mfma_f32_16x16x32_bf16 v[16:19], v[248:251], v[36:39], v[16:19]
	ds_read_b128 v[220:223], v123 offset:31232
	s_waitcnt lgkmcnt(5)
	v_mfma_f32_16x16x32_bf16 v[16:19], v[252:255], v[32:35], v[16:19]
	ds_read_b128 v[196:199], v123 offset:31296
	s_waitcnt lgkmcnt(5)
	v_pk_mul_f32 v[20:21], v[20:21], v[208:209]
	ds_read_b128 v[224:227], v97 offset:448
	v_pk_mul_f32 v[22:23], v[22:23], v[210:211]
	s_waitcnt lgkmcnt(5)
	s_nop 0
	v_mfma_f32_16x16x32_bf16 v[20:23], v[204:207], v[36:39], v[20:23]
	s_waitcnt lgkmcnt(4)
	v_mfma_f32_16x16x32_bf16 v[20:23], v[212:215], v[32:35], v[20:23]
	s_waitcnt lgkmcnt(3)
	v_pk_mul_f32 v[24:25], v[24:25], v[216:217]
	v_pk_mul_f32 v[26:27], v[26:27], v[218:219]
	s_waitcnt lgkmcnt(2)
	s_nop 0
	v_mfma_f32_16x16x32_bf16 v[24:27], v[220:223], v[36:39], v[24:27]
	s_waitcnt lgkmcnt(1)
	v_mfma_f32_16x16x32_bf16 v[24:27], v[196:199], v[32:35], v[24:27]
	s_waitcnt lgkmcnt(0)
	v_pk_mul_f32 v[28:29], v[28:29], v[224:225]
	v_pk_mul_f32 v[30:31], v[30:31], v[226:227]
	ds_read_b128 v[40:43], v123 offset:33536
	s_waitcnt lgkmcnt(0)
	v_mfma_f32_16x16x32_bf16 v[28:31], v[40:43], v[36:39], v[28:31]
	ds_read_b128 v[36:39], v123 offset:33600
	s_waitcnt lgkmcnt(0)
	s_barrier
	v_mfma_f32_16x16x32_bf16 v[28:31], v[36:39], v[32:35], v[28:31]
	s_cbranch_scc0 .LBB0_1052
